# v43 + accumulator zeroing with v_pk_mov_b32 (63 packed moves instead of 126 per unit)
# speedup vs baseline: 1.0108x; 1.0040x over previous
.LBB0_141:
	s_ashr_i32 s47, s46, 31
	s_lshl_b64 s[36:37], s[46:47], 19
	s_add_u32 s48, s20, s36
	s_addc_u32 s49, s34, s37
	s_and_b64 s[36:37], s[42:43], exec
	s_cselect_b32 s47, s49, s17
	s_cselect_b32 s78, s48, s16
	s_ashr_i32 s15, s14, 31
	s_lshl_b64 s[36:37], s[14:15], 19
	s_add_u32 s50, s39, s36
	s_addc_u32 s51, s40, s37
	s_and_b64 s[36:37], s[42:43], exec
	s_cselect_b32 s15, s51, s19
	s_cselect_b32 s79, s50, s18
	s_add_u32 s16, s16, 0x40080
	s_addc_u32 s17, s17, 0
	s_add_u32 s83, s18, 0x100
	v_mov_b32_e32 v2, 0
	s_addc_u32 s85, s19, 0
	s_mov_b32 s88, -2
	v_mov_b32_e32 v3, v2
	v_pk_mov_b32 v[4:5], v[2:3], v[2:3] op_sel:[0,1]
	v_pk_mov_b32 v[10:11], v[2:3], v[2:3] op_sel:[0,1]
	v_pk_mov_b32 v[12:13], v[2:3], v[2:3] op_sel:[0,1]
	v_pk_mov_b32 v[18:19], v[2:3], v[2:3] op_sel:[0,1]
	v_pk_mov_b32 v[20:21], v[2:3], v[2:3] op_sel:[0,1]
	v_pk_mov_b32 v[26:27], v[2:3], v[2:3] op_sel:[0,1]
	v_pk_mov_b32 v[28:29], v[2:3], v[2:3] op_sel:[0,1]
	v_pk_mov_b32 v[34:35], v[2:3], v[2:3] op_sel:[0,1]
	v_pk_mov_b32 v[36:37], v[2:3], v[2:3] op_sel:[0,1]
	v_pk_mov_b32 v[42:43], v[2:3], v[2:3] op_sel:[0,1]
	v_pk_mov_b32 v[44:45], v[2:3], v[2:3] op_sel:[0,1]
	v_pk_mov_b32 v[50:51], v[2:3], v[2:3] op_sel:[0,1]
	v_pk_mov_b32 v[52:53], v[2:3], v[2:3] op_sel:[0,1]
	v_pk_mov_b32 v[58:59], v[2:3], v[2:3] op_sel:[0,1]
	v_pk_mov_b32 v[60:61], v[2:3], v[2:3] op_sel:[0,1]
	v_pk_mov_b32 v[6:7], v[2:3], v[2:3] op_sel:[0,1]
	v_pk_mov_b32 v[8:9], v[2:3], v[2:3] op_sel:[0,1]
	v_pk_mov_b32 v[14:15], v[2:3], v[2:3] op_sel:[0,1]
	v_pk_mov_b32 v[16:17], v[2:3], v[2:3] op_sel:[0,1]
	v_pk_mov_b32 v[22:23], v[2:3], v[2:3] op_sel:[0,1]
	v_pk_mov_b32 v[24:25], v[2:3], v[2:3] op_sel:[0,1]
	v_pk_mov_b32 v[30:31], v[2:3], v[2:3] op_sel:[0,1]
	v_pk_mov_b32 v[32:33], v[2:3], v[2:3] op_sel:[0,1]
	v_pk_mov_b32 v[38:39], v[2:3], v[2:3] op_sel:[0,1]
	v_pk_mov_b32 v[40:41], v[2:3], v[2:3] op_sel:[0,1]
	v_pk_mov_b32 v[46:47], v[2:3], v[2:3] op_sel:[0,1]
	v_pk_mov_b32 v[48:49], v[2:3], v[2:3] op_sel:[0,1]
	v_pk_mov_b32 v[54:55], v[2:3], v[2:3] op_sel:[0,1]
	v_pk_mov_b32 v[56:57], v[2:3], v[2:3] op_sel:[0,1]
	v_pk_mov_b32 v[62:63], v[2:3], v[2:3] op_sel:[0,1]
	v_pk_mov_b32 v[64:65], v[2:3], v[2:3] op_sel:[0,1]
	v_pk_mov_b32 v[66:67], v[2:3], v[2:3] op_sel:[0,1]
	v_pk_mov_b32 v[68:69], v[2:3], v[2:3] op_sel:[0,1]
	v_pk_mov_b32 v[74:75], v[2:3], v[2:3] op_sel:[0,1]
	v_pk_mov_b32 v[76:77], v[2:3], v[2:3] op_sel:[0,1]
	v_pk_mov_b32 v[82:83], v[2:3], v[2:3] op_sel:[0,1]
	v_pk_mov_b32 v[84:85], v[2:3], v[2:3] op_sel:[0,1]
	v_pk_mov_b32 v[90:91], v[2:3], v[2:3] op_sel:[0,1]
	v_pk_mov_b32 v[92:93], v[2:3], v[2:3] op_sel:[0,1]
	v_pk_mov_b32 v[98:99], v[2:3], v[2:3] op_sel:[0,1]
	v_pk_mov_b32 v[100:101], v[2:3], v[2:3] op_sel:[0,1]
	v_pk_mov_b32 v[106:107], v[2:3], v[2:3] op_sel:[0,1]
	v_pk_mov_b32 v[108:109], v[2:3], v[2:3] op_sel:[0,1]
	v_pk_mov_b32 v[114:115], v[2:3], v[2:3] op_sel:[0,1]
	v_pk_mov_b32 v[116:117], v[2:3], v[2:3] op_sel:[0,1]
	v_pk_mov_b32 v[122:123], v[2:3], v[2:3] op_sel:[0,1]
	v_pk_mov_b32 v[124:125], v[2:3], v[2:3] op_sel:[0,1]
	v_pk_mov_b32 v[70:71], v[2:3], v[2:3] op_sel:[0,1]
	v_pk_mov_b32 v[72:73], v[2:3], v[2:3] op_sel:[0,1]
	v_pk_mov_b32 v[78:79], v[2:3], v[2:3] op_sel:[0,1]
	v_pk_mov_b32 v[80:81], v[2:3], v[2:3] op_sel:[0,1]
	v_pk_mov_b32 v[86:87], v[2:3], v[2:3] op_sel:[0,1]
	v_pk_mov_b32 v[88:89], v[2:3], v[2:3] op_sel:[0,1]
	v_pk_mov_b32 v[94:95], v[2:3], v[2:3] op_sel:[0,1]
	v_pk_mov_b32 v[96:97], v[2:3], v[2:3] op_sel:[0,1]
	v_pk_mov_b32 v[102:103], v[2:3], v[2:3] op_sel:[0,1]
	v_pk_mov_b32 v[104:105], v[2:3], v[2:3] op_sel:[0,1]
	v_pk_mov_b32 v[110:111], v[2:3], v[2:3] op_sel:[0,1]
	v_pk_mov_b32 v[112:113], v[2:3], v[2:3] op_sel:[0,1]
	v_pk_mov_b32 v[118:119], v[2:3], v[2:3] op_sel:[0,1]
	v_pk_mov_b32 v[120:121], v[2:3], v[2:3] op_sel:[0,1]
	v_pk_mov_b32 v[126:127], v[2:3], v[2:3] op_sel:[0,1]
	v_pk_mov_b32 v[128:129], v[2:3], v[2:3] op_sel:[0,1]

.LBB0_193:
	s_add_u32 s10, s10, 0x80
	s_addc_u32 s11, s11, 0
	s_add_u32 s14, s12, 0x100
	v_mov_b32_e32 v2, 0
	s_addc_u32 s15, s13, 0
	s_mov_b32 s12, 0
	v_mov_b32_e32 v3, v2
	v_pk_mov_b32 v[4:5], v[2:3], v[2:3] op_sel:[0,1]
	v_pk_mov_b32 v[6:7], v[2:3], v[2:3] op_sel:[0,1]
	v_pk_mov_b32 v[8:9], v[2:3], v[2:3] op_sel:[0,1]
	v_pk_mov_b32 v[18:19], v[2:3], v[2:3] op_sel:[0,1]
	v_pk_mov_b32 v[20:21], v[2:3], v[2:3] op_sel:[0,1]
	v_pk_mov_b32 v[22:23], v[2:3], v[2:3] op_sel:[0,1]
	v_pk_mov_b32 v[24:25], v[2:3], v[2:3] op_sel:[0,1]
	v_pk_mov_b32 v[34:35], v[2:3], v[2:3] op_sel:[0,1]
	v_pk_mov_b32 v[36:37], v[2:3], v[2:3] op_sel:[0,1]
	v_pk_mov_b32 v[38:39], v[2:3], v[2:3] op_sel:[0,1]
	v_pk_mov_b32 v[40:41], v[2:3], v[2:3] op_sel:[0,1]
	v_pk_mov_b32 v[50:51], v[2:3], v[2:3] op_sel:[0,1]
	v_pk_mov_b32 v[52:53], v[2:3], v[2:3] op_sel:[0,1]
	v_pk_mov_b32 v[54:55], v[2:3], v[2:3] op_sel:[0,1]
	v_pk_mov_b32 v[56:57], v[2:3], v[2:3] op_sel:[0,1]
	v_pk_mov_b32 v[10:11], v[2:3], v[2:3] op_sel:[0,1]
	v_pk_mov_b32 v[12:13], v[2:3], v[2:3] op_sel:[0,1]
	v_pk_mov_b32 v[14:15], v[2:3], v[2:3] op_sel:[0,1]
	v_pk_mov_b32 v[16:17], v[2:3], v[2:3] op_sel:[0,1]
	s_waitcnt vmcnt(0)
	v_pk_mov_b32 v[26:27], v[2:3], v[2:3] op_sel:[0,1]
	v_pk_mov_b32 v[28:29], v[2:3], v[2:3] op_sel:[0,1]
	v_pk_mov_b32 v[30:31], v[2:3], v[2:3] op_sel:[0,1]
	v_pk_mov_b32 v[32:33], v[2:3], v[2:3] op_sel:[0,1]
	v_pk_mov_b32 v[42:43], v[2:3], v[2:3] op_sel:[0,1]
	v_pk_mov_b32 v[44:45], v[2:3], v[2:3] op_sel:[0,1]
	v_pk_mov_b32 v[46:47], v[2:3], v[2:3] op_sel:[0,1]
	v_pk_mov_b32 v[48:49], v[2:3], v[2:3] op_sel:[0,1]
	v_pk_mov_b32 v[58:59], v[2:3], v[2:3] op_sel:[0,1]
	v_pk_mov_b32 v[60:61], v[2:3], v[2:3] op_sel:[0,1]
	v_pk_mov_b32 v[62:63], v[2:3], v[2:3] op_sel:[0,1]
	v_pk_mov_b32 v[64:65], v[2:3], v[2:3] op_sel:[0,1]
	v_pk_mov_b32 v[66:67], v[2:3], v[2:3] op_sel:[0,1]
	v_pk_mov_b32 v[68:69], v[2:3], v[2:3] op_sel:[0,1]
	v_pk_mov_b32 v[70:71], v[2:3], v[2:3] op_sel:[0,1]
	v_pk_mov_b32 v[72:73], v[2:3], v[2:3] op_sel:[0,1]
	v_pk_mov_b32 v[82:83], v[2:3], v[2:3] op_sel:[0,1]
	v_pk_mov_b32 v[84:85], v[2:3], v[2:3] op_sel:[0,1]
	v_pk_mov_b32 v[86:87], v[2:3], v[2:3] op_sel:[0,1]
	v_pk_mov_b32 v[88:89], v[2:3], v[2:3] op_sel:[0,1]
	v_pk_mov_b32 v[98:99], v[2:3], v[2:3] op_sel:[0,1]
	v_pk_mov_b32 v[100:101], v[2:3], v[2:3] op_sel:[0,1]
	v_pk_mov_b32 v[102:103], v[2:3], v[2:3] op_sel:[0,1]
	v_pk_mov_b32 v[104:105], v[2:3], v[2:3] op_sel:[0,1]
	v_pk_mov_b32 v[130:131], v[2:3], v[2:3] op_sel:[0,1]
	v_pk_mov_b32 v[132:133], v[2:3], v[2:3] op_sel:[0,1]
	v_pk_mov_b32 v[134:135], v[2:3], v[2:3] op_sel:[0,1]
	v_pk_mov_b32 v[136:137], v[2:3], v[2:3] op_sel:[0,1]
	v_pk_mov_b32 v[74:75], v[2:3], v[2:3] op_sel:[0,1]
	v_pk_mov_b32 v[76:77], v[2:3], v[2:3] op_sel:[0,1]
	v_pk_mov_b32 v[78:79], v[2:3], v[2:3] op_sel:[0,1]
	v_pk_mov_b32 v[80:81], v[2:3], v[2:3] op_sel:[0,1]
	v_pk_mov_b32 v[90:91], v[2:3], v[2:3] op_sel:[0,1]
	v_pk_mov_b32 v[92:93], v[2:3], v[2:3] op_sel:[0,1]
	v_pk_mov_b32 v[94:95], v[2:3], v[2:3] op_sel:[0,1]
	v_pk_mov_b32 v[96:97], v[2:3], v[2:3] op_sel:[0,1]
	v_pk_mov_b32 v[106:107], v[2:3], v[2:3] op_sel:[0,1]
	v_pk_mov_b32 v[108:109], v[2:3], v[2:3] op_sel:[0,1]
	v_pk_mov_b32 v[110:111], v[2:3], v[2:3] op_sel:[0,1]
	v_pk_mov_b32 v[112:113], v[2:3], v[2:3] op_sel:[0,1]
	v_pk_mov_b32 v[138:139], v[2:3], v[2:3] op_sel:[0,1]
	v_pk_mov_b32 v[140:141], v[2:3], v[2:3] op_sel:[0,1]
	v_pk_mov_b32 v[142:143], v[2:3], v[2:3] op_sel:[0,1]
	v_pk_mov_b32 v[144:145], v[2:3], v[2:3] op_sel:[0,1]

.LBB0_218:
	s_add_u32 s18, s18, 0x80
	s_addc_u32 s19, s19, 0
	s_add_u32 s11, s48, 0x100
	v_mov_b32_e32 v2, 0
	s_addc_u32 s15, s49, 0
	s_mov_b32 s48, 0
	v_mov_b32_e32 v3, v2
	v_pk_mov_b32 v[4:5], v[2:3], v[2:3] op_sel:[0,1]
	v_pk_mov_b32 v[6:7], v[2:3], v[2:3] op_sel:[0,1]
	v_pk_mov_b32 v[8:9], v[2:3], v[2:3] op_sel:[0,1]
	v_pk_mov_b32 v[10:11], v[2:3], v[2:3] op_sel:[0,1]
	v_pk_mov_b32 v[12:13], v[2:3], v[2:3] op_sel:[0,1]
	v_pk_mov_b32 v[14:15], v[2:3], v[2:3] op_sel:[0,1]
	v_pk_mov_b32 v[16:17], v[2:3], v[2:3] op_sel:[0,1]
	v_pk_mov_b32 v[22:23], v[2:3], v[2:3] op_sel:[0,1]
	v_pk_mov_b32 v[24:25], v[2:3], v[2:3] op_sel:[0,1]
	v_pk_mov_b32 v[30:31], v[2:3], v[2:3] op_sel:[0,1]
	v_pk_mov_b32 v[32:33], v[2:3], v[2:3] op_sel:[0,1]
	v_pk_mov_b32 v[38:39], v[2:3], v[2:3] op_sel:[0,1]
	v_pk_mov_b32 v[40:41], v[2:3], v[2:3] op_sel:[0,1]
	v_pk_mov_b32 v[46:47], v[2:3], v[2:3] op_sel:[0,1]
	v_pk_mov_b32 v[48:49], v[2:3], v[2:3] op_sel:[0,1]
	v_pk_mov_b32 v[18:19], v[2:3], v[2:3] op_sel:[0,1]
	v_pk_mov_b32 v[20:21], v[2:3], v[2:3] op_sel:[0,1]
	v_pk_mov_b32 v[26:27], v[2:3], v[2:3] op_sel:[0,1]
	v_pk_mov_b32 v[28:29], v[2:3], v[2:3] op_sel:[0,1]
	v_pk_mov_b32 v[34:35], v[2:3], v[2:3] op_sel:[0,1]
	v_pk_mov_b32 v[36:37], v[2:3], v[2:3] op_sel:[0,1]
	v_pk_mov_b32 v[42:43], v[2:3], v[2:3] op_sel:[0,1]
	v_pk_mov_b32 v[44:45], v[2:3], v[2:3] op_sel:[0,1]
	v_pk_mov_b32 v[50:51], v[2:3], v[2:3] op_sel:[0,1]
	v_pk_mov_b32 v[52:53], v[2:3], v[2:3] op_sel:[0,1]
	v_pk_mov_b32 v[54:55], v[2:3], v[2:3] op_sel:[0,1]
	v_pk_mov_b32 v[56:57], v[2:3], v[2:3] op_sel:[0,1]
	v_pk_mov_b32 v[58:59], v[2:3], v[2:3] op_sel:[0,1]
	v_pk_mov_b32 v[60:61], v[2:3], v[2:3] op_sel:[0,1]
	v_pk_mov_b32 v[62:63], v[2:3], v[2:3] op_sel:[0,1]
	v_pk_mov_b32 v[64:65], v[2:3], v[2:3] op_sel:[0,1]
	v_pk_mov_b32 v[66:67], v[2:3], v[2:3] op_sel:[0,1]
	v_pk_mov_b32 v[68:69], v[2:3], v[2:3] op_sel:[0,1]
	v_pk_mov_b32 v[70:71], v[2:3], v[2:3] op_sel:[0,1]
	v_pk_mov_b32 v[72:73], v[2:3], v[2:3] op_sel:[0,1]
	v_pk_mov_b32 v[74:75], v[2:3], v[2:3] op_sel:[0,1]
	v_pk_mov_b32 v[76:77], v[2:3], v[2:3] op_sel:[0,1]
	v_pk_mov_b32 v[78:79], v[2:3], v[2:3] op_sel:[0,1]
	v_pk_mov_b32 v[80:81], v[2:3], v[2:3] op_sel:[0,1]
	v_pk_mov_b32 v[86:87], v[2:3], v[2:3] op_sel:[0,1]
	v_pk_mov_b32 v[88:89], v[2:3], v[2:3] op_sel:[0,1]
	v_pk_mov_b32 v[94:95], v[2:3], v[2:3] op_sel:[0,1]
	v_pk_mov_b32 v[96:97], v[2:3], v[2:3] op_sel:[0,1]
	v_pk_mov_b32 v[102:103], v[2:3], v[2:3] op_sel:[0,1]
	v_pk_mov_b32 v[104:105], v[2:3], v[2:3] op_sel:[0,1]
	v_pk_mov_b32 v[110:111], v[2:3], v[2:3] op_sel:[0,1]
	v_pk_mov_b32 v[112:113], v[2:3], v[2:3] op_sel:[0,1]
	v_pk_mov_b32 v[82:83], v[2:3], v[2:3] op_sel:[0,1]
	v_pk_mov_b32 v[84:85], v[2:3], v[2:3] op_sel:[0,1]
	v_pk_mov_b32 v[90:91], v[2:3], v[2:3] op_sel:[0,1]
	v_pk_mov_b32 v[92:93], v[2:3], v[2:3] op_sel:[0,1]
	v_pk_mov_b32 v[98:99], v[2:3], v[2:3] op_sel:[0,1]
	v_pk_mov_b32 v[100:101], v[2:3], v[2:3] op_sel:[0,1]
	v_pk_mov_b32 v[106:107], v[2:3], v[2:3] op_sel:[0,1]
	v_pk_mov_b32 v[108:109], v[2:3], v[2:3] op_sel:[0,1]
	v_pk_mov_b32 v[114:115], v[2:3], v[2:3] op_sel:[0,1]
	v_pk_mov_b32 v[116:117], v[2:3], v[2:3] op_sel:[0,1]
	v_pk_mov_b32 v[118:119], v[2:3], v[2:3] op_sel:[0,1]
	v_pk_mov_b32 v[120:121], v[2:3], v[2:3] op_sel:[0,1]
	v_pk_mov_b32 v[122:123], v[2:3], v[2:3] op_sel:[0,1]
	v_pk_mov_b32 v[124:125], v[2:3], v[2:3] op_sel:[0,1]
	v_pk_mov_b32 v[126:127], v[2:3], v[2:3] op_sel:[0,1]
	v_pk_mov_b32 v[128:129], v[2:3], v[2:3] op_sel:[0,1]

.LBB0_436:
	s_ashr_i32 s9, s8, 31
	s_lshl_b64 s[14:15], s[8:9], 19
	s_cmp_eq_u32 s75, 0
	s_cselect_b32 s36, s20, s16
	s_cselect_b32 s9, s39, s17
	s_cselect_b32 s37, s16, s20
	s_cselect_b32 s46, s17, s39
	s_add_u32 s50, s36, s14
	s_addc_u32 s51, s9, s15
	s_and_b64 s[14:15], s[42:43], exec
	s_cselect_b32 s9, s51, s11
	s_cselect_b32 s45, s50, s10
	s_waitcnt lgkmcnt(0)
	s_ashr_i32 s49, s48, 31
	s_lshl_b64 s[14:15], s[48:49], 19
	s_add_u32 s52, s37, s14
	s_addc_u32 s53, s46, s15
	s_and_b64 s[14:15], s[42:43], exec
	s_cselect_b32 s46, s53, s13
	s_cselect_b32 s47, s52, s12
	s_add_u32 s10, s10, 0x40080
	s_addc_u32 s11, s11, 0
	s_add_u32 s49, s12, 0x100
	v_mov_b32_e32 v2, 0
	s_addc_u32 s77, s13, 0
	s_mov_b32 s78, -2
	v_mov_b32_e32 v3, v2
	v_pk_mov_b32 v[4:5], v[2:3], v[2:3] op_sel:[0,1]
	v_pk_mov_b32 v[6:7], v[2:3], v[2:3] op_sel:[0,1]
	v_pk_mov_b32 v[8:9], v[2:3], v[2:3] op_sel:[0,1]
	v_pk_mov_b32 v[18:19], v[2:3], v[2:3] op_sel:[0,1]
	v_pk_mov_b32 v[20:21], v[2:3], v[2:3] op_sel:[0,1]
	v_pk_mov_b32 v[22:23], v[2:3], v[2:3] op_sel:[0,1]
	v_pk_mov_b32 v[24:25], v[2:3], v[2:3] op_sel:[0,1]
	v_pk_mov_b32 v[34:35], v[2:3], v[2:3] op_sel:[0,1]
	v_pk_mov_b32 v[36:37], v[2:3], v[2:3] op_sel:[0,1]
	v_pk_mov_b32 v[38:39], v[2:3], v[2:3] op_sel:[0,1]
	v_pk_mov_b32 v[40:41], v[2:3], v[2:3] op_sel:[0,1]
	v_pk_mov_b32 v[50:51], v[2:3], v[2:3] op_sel:[0,1]
	v_pk_mov_b32 v[52:53], v[2:3], v[2:3] op_sel:[0,1]
	v_pk_mov_b32 v[54:55], v[2:3], v[2:3] op_sel:[0,1]
	v_pk_mov_b32 v[56:57], v[2:3], v[2:3] op_sel:[0,1]
	v_pk_mov_b32 v[10:11], v[2:3], v[2:3] op_sel:[0,1]
	v_pk_mov_b32 v[12:13], v[2:3], v[2:3] op_sel:[0,1]
	v_pk_mov_b32 v[14:15], v[2:3], v[2:3] op_sel:[0,1]
	v_pk_mov_b32 v[16:17], v[2:3], v[2:3] op_sel:[0,1]
	v_pk_mov_b32 v[26:27], v[2:3], v[2:3] op_sel:[0,1]
	v_pk_mov_b32 v[28:29], v[2:3], v[2:3] op_sel:[0,1]
	v_pk_mov_b32 v[30:31], v[2:3], v[2:3] op_sel:[0,1]
	v_pk_mov_b32 v[32:33], v[2:3], v[2:3] op_sel:[0,1]
	v_pk_mov_b32 v[42:43], v[2:3], v[2:3] op_sel:[0,1]
	v_pk_mov_b32 v[44:45], v[2:3], v[2:3] op_sel:[0,1]
	v_pk_mov_b32 v[46:47], v[2:3], v[2:3] op_sel:[0,1]
	v_pk_mov_b32 v[48:49], v[2:3], v[2:3] op_sel:[0,1]
	v_pk_mov_b32 v[58:59], v[2:3], v[2:3] op_sel:[0,1]
	v_pk_mov_b32 v[60:61], v[2:3], v[2:3] op_sel:[0,1]
	v_pk_mov_b32 v[62:63], v[2:3], v[2:3] op_sel:[0,1]
	v_pk_mov_b32 v[64:65], v[2:3], v[2:3] op_sel:[0,1]
	v_pk_mov_b32 v[66:67], v[2:3], v[2:3] op_sel:[0,1]
	v_pk_mov_b32 v[68:69], v[2:3], v[2:3] op_sel:[0,1]
	v_pk_mov_b32 v[70:71], v[2:3], v[2:3] op_sel:[0,1]
	v_pk_mov_b32 v[72:73], v[2:3], v[2:3] op_sel:[0,1]
	v_pk_mov_b32 v[82:83], v[2:3], v[2:3] op_sel:[0,1]
	v_pk_mov_b32 v[84:85], v[2:3], v[2:3] op_sel:[0,1]
	v_pk_mov_b32 v[86:87], v[2:3], v[2:3] op_sel:[0,1]
	v_pk_mov_b32 v[88:89], v[2:3], v[2:3] op_sel:[0,1]
	v_pk_mov_b32 v[98:99], v[2:3], v[2:3] op_sel:[0,1]
	v_pk_mov_b32 v[100:101], v[2:3], v[2:3] op_sel:[0,1]
	v_pk_mov_b32 v[102:103], v[2:3], v[2:3] op_sel:[0,1]
	v_pk_mov_b32 v[104:105], v[2:3], v[2:3] op_sel:[0,1]
	v_pk_mov_b32 v[114:115], v[2:3], v[2:3] op_sel:[0,1]
	v_pk_mov_b32 v[116:117], v[2:3], v[2:3] op_sel:[0,1]
	v_pk_mov_b32 v[118:119], v[2:3], v[2:3] op_sel:[0,1]
	v_pk_mov_b32 v[120:121], v[2:3], v[2:3] op_sel:[0,1]
	v_pk_mov_b32 v[74:75], v[2:3], v[2:3] op_sel:[0,1]
	v_pk_mov_b32 v[76:77], v[2:3], v[2:3] op_sel:[0,1]
	v_pk_mov_b32 v[78:79], v[2:3], v[2:3] op_sel:[0,1]
	v_pk_mov_b32 v[80:81], v[2:3], v[2:3] op_sel:[0,1]
	v_pk_mov_b32 v[90:91], v[2:3], v[2:3] op_sel:[0,1]
	v_pk_mov_b32 v[92:93], v[2:3], v[2:3] op_sel:[0,1]
	v_pk_mov_b32 v[94:95], v[2:3], v[2:3] op_sel:[0,1]
	v_pk_mov_b32 v[96:97], v[2:3], v[2:3] op_sel:[0,1]
	v_pk_mov_b32 v[106:107], v[2:3], v[2:3] op_sel:[0,1]
	v_pk_mov_b32 v[108:109], v[2:3], v[2:3] op_sel:[0,1]
	v_pk_mov_b32 v[110:111], v[2:3], v[2:3] op_sel:[0,1]
	v_pk_mov_b32 v[112:113], v[2:3], v[2:3] op_sel:[0,1]
	v_pk_mov_b32 v[122:123], v[2:3], v[2:3] op_sel:[0,1]
	v_pk_mov_b32 v[124:125], v[2:3], v[2:3] op_sel:[0,1]
	v_pk_mov_b32 v[126:127], v[2:3], v[2:3] op_sel:[0,1]
	v_pk_mov_b32 v[128:129], v[2:3], v[2:3] op_sel:[0,1]

.LBB0_492:
	s_ashr_i32 s51, s50, 31
	s_lshl_b64 s[18:19], s[50:51], 19
	s_add_u32 s52, s20, s18
	s_addc_u32 s53, s39, s19
	s_and_b64 s[18:19], s[42:43], exec
	s_cselect_b32 s11, s53, s15
	s_cselect_b32 s13, s52, s14
	s_waitcnt lgkmcnt(0)
	s_ashr_i32 s49, s48, 31
	s_lshl_b64 s[18:19], s[48:49], 19
	s_add_u32 s54, s34, s18
	s_addc_u32 s55, s70, s19
	s_and_b64 s[18:19], s[42:43], exec
	s_cselect_b32 s40, s55, s17
	s_cselect_b32 s41, s54, s16
	s_add_u32 s14, s14, 0x40080
	s_addc_u32 s15, s15, 0
	s_add_u32 s44, s16, 0x100
	v_mov_b32_e32 v2, 0
	s_addc_u32 s45, s17, 0
	s_mov_b32 s46, -2
	v_mov_b32_e32 v3, v2
	v_pk_mov_b32 v[4:5], v[2:3], v[2:3] op_sel:[0,1]
	v_pk_mov_b32 v[6:7], v[2:3], v[2:3] op_sel:[0,1]
	v_pk_mov_b32 v[8:9], v[2:3], v[2:3] op_sel:[0,1]
	v_pk_mov_b32 v[18:19], v[2:3], v[2:3] op_sel:[0,1]
	v_pk_mov_b32 v[20:21], v[2:3], v[2:3] op_sel:[0,1]
	v_pk_mov_b32 v[22:23], v[2:3], v[2:3] op_sel:[0,1]
	v_pk_mov_b32 v[24:25], v[2:3], v[2:3] op_sel:[0,1]
	v_pk_mov_b32 v[34:35], v[2:3], v[2:3] op_sel:[0,1]
	v_pk_mov_b32 v[36:37], v[2:3], v[2:3] op_sel:[0,1]
	v_pk_mov_b32 v[38:39], v[2:3], v[2:3] op_sel:[0,1]
	v_pk_mov_b32 v[40:41], v[2:3], v[2:3] op_sel:[0,1]
	v_pk_mov_b32 v[50:51], v[2:3], v[2:3] op_sel:[0,1]
	v_pk_mov_b32 v[52:53], v[2:3], v[2:3] op_sel:[0,1]
	v_pk_mov_b32 v[54:55], v[2:3], v[2:3] op_sel:[0,1]
	v_pk_mov_b32 v[56:57], v[2:3], v[2:3] op_sel:[0,1]
	v_pk_mov_b32 v[10:11], v[2:3], v[2:3] op_sel:[0,1]
	v_pk_mov_b32 v[12:13], v[2:3], v[2:3] op_sel:[0,1]
	v_pk_mov_b32 v[14:15], v[2:3], v[2:3] op_sel:[0,1]
	v_pk_mov_b32 v[16:17], v[2:3], v[2:3] op_sel:[0,1]
	v_pk_mov_b32 v[26:27], v[2:3], v[2:3] op_sel:[0,1]
	v_pk_mov_b32 v[28:29], v[2:3], v[2:3] op_sel:[0,1]
	v_pk_mov_b32 v[30:31], v[2:3], v[2:3] op_sel:[0,1]
	v_pk_mov_b32 v[32:33], v[2:3], v[2:3] op_sel:[0,1]
	v_pk_mov_b32 v[42:43], v[2:3], v[2:3] op_sel:[0,1]
	v_pk_mov_b32 v[44:45], v[2:3], v[2:3] op_sel:[0,1]
	v_pk_mov_b32 v[46:47], v[2:3], v[2:3] op_sel:[0,1]
	v_pk_mov_b32 v[48:49], v[2:3], v[2:3] op_sel:[0,1]
	v_pk_mov_b32 v[58:59], v[2:3], v[2:3] op_sel:[0,1]
	v_pk_mov_b32 v[60:61], v[2:3], v[2:3] op_sel:[0,1]
	v_pk_mov_b32 v[62:63], v[2:3], v[2:3] op_sel:[0,1]
	v_pk_mov_b32 v[64:65], v[2:3], v[2:3] op_sel:[0,1]
	v_pk_mov_b32 v[66:67], v[2:3], v[2:3] op_sel:[0,1]
	v_pk_mov_b32 v[68:69], v[2:3], v[2:3] op_sel:[0,1]
	v_pk_mov_b32 v[70:71], v[2:3], v[2:3] op_sel:[0,1]
	v_pk_mov_b32 v[72:73], v[2:3], v[2:3] op_sel:[0,1]
	v_pk_mov_b32 v[82:83], v[2:3], v[2:3] op_sel:[0,1]
	v_pk_mov_b32 v[84:85], v[2:3], v[2:3] op_sel:[0,1]
	v_pk_mov_b32 v[86:87], v[2:3], v[2:3] op_sel:[0,1]
	v_pk_mov_b32 v[88:89], v[2:3], v[2:3] op_sel:[0,1]
	v_pk_mov_b32 v[98:99], v[2:3], v[2:3] op_sel:[0,1]
	v_pk_mov_b32 v[100:101], v[2:3], v[2:3] op_sel:[0,1]
	v_pk_mov_b32 v[102:103], v[2:3], v[2:3] op_sel:[0,1]
	v_pk_mov_b32 v[104:105], v[2:3], v[2:3] op_sel:[0,1]
	v_pk_mov_b32 v[114:115], v[2:3], v[2:3] op_sel:[0,1]
	v_pk_mov_b32 v[116:117], v[2:3], v[2:3] op_sel:[0,1]
	v_pk_mov_b32 v[118:119], v[2:3], v[2:3] op_sel:[0,1]
	v_pk_mov_b32 v[120:121], v[2:3], v[2:3] op_sel:[0,1]
	v_pk_mov_b32 v[74:75], v[2:3], v[2:3] op_sel:[0,1]
	v_pk_mov_b32 v[76:77], v[2:3], v[2:3] op_sel:[0,1]
	v_pk_mov_b32 v[78:79], v[2:3], v[2:3] op_sel:[0,1]
	v_pk_mov_b32 v[80:81], v[2:3], v[2:3] op_sel:[0,1]
	v_pk_mov_b32 v[90:91], v[2:3], v[2:3] op_sel:[0,1]
	v_pk_mov_b32 v[92:93], v[2:3], v[2:3] op_sel:[0,1]
	v_pk_mov_b32 v[94:95], v[2:3], v[2:3] op_sel:[0,1]
	v_pk_mov_b32 v[96:97], v[2:3], v[2:3] op_sel:[0,1]
	v_pk_mov_b32 v[106:107], v[2:3], v[2:3] op_sel:[0,1]
	v_pk_mov_b32 v[108:109], v[2:3], v[2:3] op_sel:[0,1]
	v_pk_mov_b32 v[110:111], v[2:3], v[2:3] op_sel:[0,1]
	v_pk_mov_b32 v[112:113], v[2:3], v[2:3] op_sel:[0,1]
	v_pk_mov_b32 v[122:123], v[2:3], v[2:3] op_sel:[0,1]
	v_pk_mov_b32 v[124:125], v[2:3], v[2:3] op_sel:[0,1]
	v_pk_mov_b32 v[126:127], v[2:3], v[2:3] op_sel:[0,1]
	v_pk_mov_b32 v[128:129], v[2:3], v[2:3] op_sel:[0,1]
